# MLA: next sub-block's sub/exp2 and the row-sum tree interleaved into the PV MFMA shadows (zero-fill / full-sum stubs on the skipped-block path)
# speedup vs baseline: 1.0266x; 1.0033x over previous
; DI void mla2_item(PP p, int item, unsigned char* lds) {
;     ...
;                 const float mnew = fmaxf(mrun, mx);
;                 const float alpha = __builtin_amdgcn_exp2f(mrun - mnew);
;                 float rsum = 0.f;
; #pragma unroll
;                 for (int kb = 0; kb < 4; ++kb)
; #pragma unroll
;                     for (int r = 0; r < 16; ++r) { sc[kb][r] = __builtin_amdgcn_exp2f(sc[kb][r] - mnew); rsum += sc[kb][r]; }
;                 const bool grew = mnew > mrun;
;                 lrun = lrun * alpha + rsum; mrun = mnew;
.LBB0_238:
	s_or_b64 exec, exec, s[50:51]
	v_fmac_f32_e32 v3, v232, v2
	v_mov_b32_e32 v238, v1
	v_mov_b32_e32 v232, v3

; DI f32x16 mfma32(bf16x8 a, bf16x8 b, f32x16 c) { return __builtin_amdgcn_mfma_f32_32x32x16_bf16(a, b, c, 0, 0, 0); }
; DI void mla2_item(PP p, int item, unsigned char* lds) {
;     ...
; #pragma unroll
;                 for (int kb = 0; kb < 4; ++kb)
; #pragma unroll
;                     for (int r = 0; r < 16; ++r) { sc[kb][r] = __builtin_amdgcn_exp2f(sc[kb][r] - mnew); rsum += sc[kb][r]; }
;                 const bool grew = mnew > mrun;
;                 lrun = lrun * alpha + rsum; mrun = mnew;
;                 if (__any(grew)) { o[0] = o[0] * alpha; o[1] = o[1] * alpha; }
; #pragma unroll
;                 for (int kb = 0; kb < 4; ++kb) {
;                     if (kb <= kbmax) {
; #pragma unroll
;                         for (int ks = 0; ks < 2; ++ks) {
;                             const bf16x8 pb = pack_step(sc[kb], ks);
; #pragma unroll
;                             for (int dvb = 0; dvb < 2; ++dvb)
;                                 o[dvb] = mfma32(ld16(Vl + (dvb * 32 + l31) * V2STR + kb * 32 + 16 * ks + 8 * hh), pb, o[dvb]);
;                         }
;                     }
;                 }
.LBB0_252:
	v_sub_f32_e32 v3, v80, v1
	v_sub_f32_e32 v4, v81, v1
	v_sub_f32_e32 v5, v82, v1
	v_sub_f32_e32 v6, v83, v1
	v_sub_f32_e32 v7, v84, v1
	v_sub_f32_e32 v8, v85, v1
	v_sub_f32_e32 v9, v86, v1
	v_sub_f32_e32 v10, v87, v1
	v_exp_f32_e32 v3, v3
	v_exp_f32_e32 v4, v4
	v_exp_f32_e32 v5, v5
	v_exp_f32_e32 v6, v6
	v_exp_f32_e32 v7, v7
	v_exp_f32_e32 v8, v8
	v_exp_f32_e32 v9, v9
	v_exp_f32_e32 v10, v10
	v_sub_f32_e32 v86, v99, v1
	v_add_u32_e32 v99, v234, v230
	v_sub_f32_e32 v14, v91, v1
	v_sub_f32_e32 v15, v92, v1
	v_sub_f32_e32 v80, v93, v1
	v_sub_f32_e32 v81, v94, v1
	v_sub_f32_e32 v82, v95, v1
	v_sub_f32_e32 v83, v96, v1
	v_sub_f32_e32 v84, v97, v1
	v_sub_f32_e32 v85, v98, v1
	v_sub_f32_e32 v91, v104, v1
	v_sub_f32_e32 v92, v105, v1
	v_sub_f32_e32 v93, v106, v1
	v_sub_f32_e32 v94, v107, v1
	v_sub_f32_e32 v95, v108, v1
	v_sub_f32_e32 v96, v109, v1
	v_sub_f32_e32 v97, v110, v1
	v_sub_f32_e32 v98, v111, v1
	ds_read_b128 v[104:107], v99 offset:26624
	ds_read_b128 v[108:111], v99 offset:26656
	v_sub_f32_e32 v11, v88, v1
	v_sub_f32_e32 v12, v89, v1
	v_sub_f32_e32 v13, v90, v1
	v_sub_f32_e32 v87, v100, v1
	v_sub_f32_e32 v88, v101, v1
	v_sub_f32_e32 v89, v102, v1
	v_sub_f32_e32 v90, v103, v1
	v_cvt_pk_bf16_f32 v100, v3, v4
	v_cvt_pk_bf16_f32 v101, v5, v6
	v_cvt_pk_bf16_f32 v102, v7, v8
	v_cvt_pk_bf16_f32 v103, v9, v10
	v_exp_f32_e32 v11, v11
	v_exp_f32_e32 v12, v12
	s_waitcnt lgkmcnt(1)
	v_mfma_f32_32x32x16_bf16 v[32:47], v[104:107], v[100:103], v[32:47]
	ds_read_b128 v[104:107], v99 offset:35328
	v_exp_f32_e32 v13, v13
	v_exp_f32_e32 v14, v14
	v_exp_f32_e32 v15, v15
	v_exp_f32_e32 v80, v80
	v_exp_f32_e32 v81, v81
	v_exp_f32_e32 v82, v82
	s_waitcnt lgkmcnt(0)
	v_mfma_f32_32x32x16_bf16 v[16:31], v[104:107], v[100:103], v[16:31]
	ds_read_b128 v[104:107], v99 offset:35360
	v_cvt_pk_bf16_f32 v100, v11, v12
	v_cvt_pk_bf16_f32 v101, v13, v14
	v_cvt_pk_bf16_f32 v102, v15, v80
	v_cvt_pk_bf16_f32 v103, v81, v82
	v_exp_f32_e32 v83, v83
	v_exp_f32_e32 v84, v84
	v_mfma_f32_32x32x16_bf16 v[32:47], v[108:111], v[100:103], v[32:47]
	v_exp_f32_e32 v85, v85
	v_exp_f32_e32 v86, v86
	v_exp_f32_e32 v87, v87
	v_exp_f32_e32 v88, v88
	v_exp_f32_e32 v89, v89
	v_exp_f32_e32 v90, v90
	v_exp_f32_e32 v91, v91
	s_waitcnt lgkmcnt(0)
	v_mfma_f32_32x32x16_bf16 v[16:31], v[104:107], v[100:103], v[16:31]
	v_exp_f32_e32 v92, v92
	v_exp_f32_e32 v93, v93
	v_exp_f32_e32 v94, v94
	v_exp_f32_e32 v95, v95
	v_exp_f32_e32 v96, v96
	v_exp_f32_e32 v97, v97
	v_exp_f32_e32 v98, v98
	s_and_saveexec_b64 s[56:57], s[52:53]
	s_cbranch_execz .Lpv_skip_5
	ds_read_b128 v[100:103], v99 offset:26688
	ds_read_b128 v[212:215], v99 offset:35392
	ds_read_b128 v[216:219], v99 offset:26720
	ds_read_b128 v[220:223], v99 offset:35424
	v_cvt_pk_bf16_f32 v104, v83, v84
	v_cvt_pk_bf16_f32 v105, v85, v86
	v_cvt_pk_bf16_f32 v106, v87, v88
	v_cvt_pk_bf16_f32 v107, v89, v90
	s_waitcnt lgkmcnt(3)
	s_nop 0
	v_mfma_f32_32x32x16_bf16 v[32:47], v[100:103], v[104:107], v[32:47]
	v_sub_f32_e32 v48, v48, v1
	v_sub_f32_e32 v49, v49, v1
	v_sub_f32_e32 v50, v50, v1
	v_sub_f32_e32 v51, v51, v1
	v_sub_f32_e32 v52, v52, v1
	v_sub_f32_e32 v53, v53, v1
	v_sub_f32_e32 v54, v54, v1
	v_sub_f32_e32 v55, v55, v1
	s_waitcnt lgkmcnt(2)
	v_mfma_f32_32x32x16_bf16 v[16:31], v[212:215], v[104:107], v[16:31]
	v_sub_f32_e32 v56, v56, v1
	v_sub_f32_e32 v57, v57, v1
	v_sub_f32_e32 v58, v58, v1
	v_sub_f32_e32 v59, v59, v1
	v_sub_f32_e32 v60, v60, v1
	v_sub_f32_e32 v61, v61, v1
	v_sub_f32_e32 v62, v62, v1
	v_sub_f32_e32 v63, v63, v1
	v_cvt_pk_bf16_f32 v104, v91, v92
	v_cvt_pk_bf16_f32 v105, v93, v94
	v_cvt_pk_bf16_f32 v106, v95, v96
	v_cvt_pk_bf16_f32 v107, v97, v98
	s_waitcnt lgkmcnt(1)
	s_nop 0
	v_mfma_f32_32x32x16_bf16 v[32:47], v[216:219], v[104:107], v[32:47]
	v_exp_f32_e32 v48, v48
	v_exp_f32_e32 v49, v49
	v_exp_f32_e32 v50, v50
	v_exp_f32_e32 v51, v51
	v_exp_f32_e32 v52, v52
	v_exp_f32_e32 v53, v53
	v_exp_f32_e32 v54, v54
	v_exp_f32_e32 v55, v55
	s_waitcnt lgkmcnt(0)
	v_mfma_f32_32x32x16_bf16 v[16:31], v[220:223], v[104:107], v[16:31]
	v_exp_f32_e32 v56, v56
	v_exp_f32_e32 v57, v57
	v_exp_f32_e32 v58, v58
	v_exp_f32_e32 v59, v59
	v_exp_f32_e32 v60, v60
	v_exp_f32_e32 v61, v61
	v_exp_f32_e32 v62, v62
	v_exp_f32_e32 v63, v63
; DI f32x16 mfma32(bf16x8 a, bf16x8 b, f32x16 c) { return __builtin_amdgcn_mfma_f32_32x32x16_bf16(a, b, c, 0, 0, 0); }
; DI void mla2_item(PP p, int item, unsigned char* lds) {
;     ...
; #pragma unroll
;                 for (int kb = 0; kb < 4; ++kb)
; #pragma unroll
;                     for (int r = 0; r < 16; ++r) { sc[kb][r] = __builtin_amdgcn_exp2f(sc[kb][r] - mnew); rsum += sc[kb][r]; }
;                 const bool grew = mnew > mrun;
;                 lrun = lrun * alpha + rsum; mrun = mnew;
;                 if (__any(grew)) { o[0] = o[0] * alpha; o[1] = o[1] * alpha; }
; #pragma unroll
;                 for (int kb = 0; kb < 4; ++kb) {
;                     if (kb <= kbmax) {
; #pragma unroll
;                         for (int ks = 0; ks < 2; ++ks) {
;                             const bf16x8 pb = pack_step(sc[kb], ks);
; #pragma unroll
;                             for (int dvb = 0; dvb < 2; ++dvb)
;                                 o[dvb] = mfma32(ld16(Vl + (dvb * 32 + l31) * V2STR + kb * 32 + 16 * ks + 8 * hh), pb, o[dvb]);
;                         }
;                     }
;                 }
.LBB0_254:
	s_or_b64 exec, exec, s[56:57]
	s_and_saveexec_b64 s[52:53], s[50:51]
	s_cbranch_execz .Lpv_skip_4
	ds_read_b128 v[100:103], v99 offset:26752
	ds_read_b128 v[212:215], v99 offset:35456
	ds_read_b128 v[216:219], v99 offset:26784
	ds_read_b128 v[220:223], v99 offset:35488
	v_cvt_pk_bf16_f32 v104, v48, v49
	v_cvt_pk_bf16_f32 v105, v50, v51
	v_cvt_pk_bf16_f32 v106, v52, v53
	v_cvt_pk_bf16_f32 v107, v54, v55
	s_waitcnt lgkmcnt(3)
	s_nop 0
	v_mfma_f32_32x32x16_bf16 v[32:47], v[100:103], v[104:107], v[32:47]
	v_sub_f32_e32 v64, v64, v1
	v_sub_f32_e32 v65, v65, v1
	v_sub_f32_e32 v66, v66, v1
	v_sub_f32_e32 v67, v67, v1
	v_sub_f32_e32 v68, v68, v1
	v_sub_f32_e32 v69, v69, v1
	v_sub_f32_e32 v70, v70, v1
	v_sub_f32_e32 v71, v71, v1
	s_waitcnt lgkmcnt(2)
	v_mfma_f32_32x32x16_bf16 v[16:31], v[212:215], v[104:107], v[16:31]
	v_sub_f32_e32 v72, v72, v1
	v_sub_f32_e32 v73, v73, v1
	v_sub_f32_e32 v74, v74, v1
	v_sub_f32_e32 v75, v75, v1
	v_sub_f32_e32 v76, v76, v1
	v_sub_f32_e32 v77, v77, v1
	v_sub_f32_e32 v78, v78, v1
	v_sub_f32_e32 v79, v79, v1
	v_cvt_pk_bf16_f32 v104, v56, v57
	v_cvt_pk_bf16_f32 v105, v58, v59
	v_cvt_pk_bf16_f32 v106, v60, v61
	v_cvt_pk_bf16_f32 v107, v62, v63
	s_waitcnt lgkmcnt(1)
	s_nop 0
	v_mfma_f32_32x32x16_bf16 v[32:47], v[216:219], v[104:107], v[32:47]
	v_exp_f32_e32 v64, v64
	v_exp_f32_e32 v65, v65
	v_exp_f32_e32 v66, v66
	v_exp_f32_e32 v67, v67
	v_exp_f32_e32 v68, v68
	v_exp_f32_e32 v69, v69
	v_exp_f32_e32 v70, v70
	v_exp_f32_e32 v71, v71
	s_waitcnt lgkmcnt(0)
	v_mfma_f32_32x32x16_bf16 v[16:31], v[220:223], v[104:107], v[16:31]
	v_exp_f32_e32 v72, v72
	v_exp_f32_e32 v73, v73
	v_exp_f32_e32 v74, v74
	v_exp_f32_e32 v75, v75
	v_exp_f32_e32 v76, v76
	v_exp_f32_e32 v77, v77
	v_exp_f32_e32 v78, v78
	v_exp_f32_e32 v79, v79
.LBB0_256:
	s_or_b64 exec, exec, s[52:53]
	s_and_saveexec_b64 s[50:51], s[48:49]
	s_cbranch_execz .Lrs_skip_1
	ds_read_b128 v[100:103], v99 offset:26816
	ds_read_b128 v[212:215], v99 offset:35520
	ds_read_b128 v[216:219], v99 offset:26848
	ds_read_b128 v[220:223], v99 offset:35552
	v_cvt_pk_bf16_f32 v104, v64, v65
	v_cvt_pk_bf16_f32 v105, v66, v67
	v_cvt_pk_bf16_f32 v106, v68, v69
	v_cvt_pk_bf16_f32 v107, v70, v71
	s_waitcnt lgkmcnt(3)
	s_nop 0
	v_mfma_f32_32x32x16_bf16 v[32:47], v[100:103], v[104:107], v[32:47]
	v_add_f32_e32 v3, v3, v4
	v_add_f32_e32 v5, v5, v6
	v_add_f32_e32 v7, v7, v8
	v_add_f32_e32 v9, v9, v10
	v_add_f32_e32 v11, v11, v12
	v_add_f32_e32 v13, v13, v14
	v_add_f32_e32 v15, v15, v80
	v_add_f32_e32 v81, v81, v82
	s_waitcnt lgkmcnt(2)
	v_mfma_f32_32x32x16_bf16 v[16:31], v[212:215], v[104:107], v[16:31]
	v_add_f32_e32 v83, v83, v84
	v_add_f32_e32 v85, v85, v86
	v_add_f32_e32 v87, v87, v88
	v_add_f32_e32 v89, v89, v90
	v_add_f32_e32 v91, v91, v92
	v_add_f32_e32 v93, v93, v94
	v_add_f32_e32 v95, v95, v96
	v_add_f32_e32 v97, v97, v98
	v_cvt_pk_bf16_f32 v104, v72, v73
	v_cvt_pk_bf16_f32 v105, v74, v75
	v_cvt_pk_bf16_f32 v106, v76, v77
	v_cvt_pk_bf16_f32 v107, v78, v79
	s_waitcnt lgkmcnt(1)
	s_nop 0
	v_mfma_f32_32x32x16_bf16 v[32:47], v[216:219], v[104:107], v[32:47]
	v_add_f32_e32 v48, v48, v49
	v_add_f32_e32 v50, v50, v51
	v_add_f32_e32 v52, v52, v53
	v_add_f32_e32 v54, v54, v55
	v_add_f32_e32 v56, v56, v57
	v_add_f32_e32 v58, v58, v59
	v_add_f32_e32 v60, v60, v61
	v_add_f32_e32 v62, v62, v63
	s_waitcnt lgkmcnt(0)
	v_mfma_f32_32x32x16_bf16 v[16:31], v[220:223], v[104:107], v[16:31]
	v_add_f32_e32 v64, v64, v65
	v_add_f32_e32 v66, v66, v67
	v_add_f32_e32 v68, v68, v69
	v_add_f32_e32 v70, v70, v71
	v_add_f32_e32 v72, v72, v73
	v_add_f32_e32 v74, v74, v75
	v_add_f32_e32 v76, v76, v77
	v_add_f32_e32 v78, v78, v79
	v_add_f32_e32 v3, v3, v5
	v_add_f32_e32 v7, v7, v9
	v_add_f32_e32 v11, v11, v13
	v_add_f32_e32 v15, v15, v81
	v_add_f32_e32 v83, v83, v85
	v_add_f32_e32 v87, v87, v89
	v_add_f32_e32 v91, v91, v93
	v_add_f32_e32 v95, v95, v97
	v_add_f32_e32 v48, v48, v50
	v_add_f32_e32 v52, v52, v54
	v_add_f32_e32 v56, v56, v58
	v_add_f32_e32 v60, v60, v62
	v_add_f32_e32 v64, v64, v66
	v_add_f32_e32 v68, v68, v70
	v_add_f32_e32 v72, v72, v74
	v_add_f32_e32 v76, v76, v78
	v_add_f32_e32 v3, v3, v7
	v_add_f32_e32 v11, v11, v15
	v_add_f32_e32 v83, v83, v87
	v_add_f32_e32 v91, v91, v95
	v_add_f32_e32 v48, v48, v52
	v_add_f32_e32 v56, v56, v60
	v_add_f32_e32 v64, v64, v68
	v_add_f32_e32 v72, v72, v76
	v_add_f32_e32 v3, v3, v11
	v_add_f32_e32 v83, v83, v91
	v_add_f32_e32 v48, v48, v56
	v_add_f32_e32 v64, v64, v72
	v_add_f32_e32 v3, v3, v83
	v_add_f32_e32 v48, v48, v64
	v_add_f32_e32 v3, v3, v48

.LBB0_271:
	v_sub_f32_e32 v3, v80, v1
	v_sub_f32_e32 v4, v81, v1
	v_sub_f32_e32 v5, v82, v1
	v_sub_f32_e32 v6, v83, v1
	v_sub_f32_e32 v7, v84, v1
	v_sub_f32_e32 v8, v85, v1
	v_sub_f32_e32 v9, v86, v1
	v_sub_f32_e32 v10, v87, v1
	v_exp_f32_e32 v3, v3
	v_exp_f32_e32 v4, v4
	v_exp_f32_e32 v5, v5
	v_exp_f32_e32 v6, v6
	v_exp_f32_e32 v7, v7
	v_exp_f32_e32 v8, v8
	v_exp_f32_e32 v9, v9
	v_exp_f32_e32 v10, v10
	v_sub_f32_e32 v86, v99, v1
	v_add_u32_e32 v99, v239, v230
	v_sub_f32_e32 v14, v91, v1
	v_sub_f32_e32 v15, v92, v1
	v_sub_f32_e32 v80, v93, v1
	v_sub_f32_e32 v81, v94, v1
	v_sub_f32_e32 v82, v95, v1
	v_sub_f32_e32 v83, v96, v1
	v_sub_f32_e32 v84, v97, v1
	v_sub_f32_e32 v85, v98, v1
	v_sub_f32_e32 v91, v104, v1
	v_sub_f32_e32 v92, v105, v1
	v_sub_f32_e32 v93, v106, v1
	v_sub_f32_e32 v94, v107, v1
	v_sub_f32_e32 v95, v108, v1
	v_sub_f32_e32 v96, v109, v1
	v_sub_f32_e32 v97, v110, v1
	v_sub_f32_e32 v98, v111, v1
	ds_read_b128 v[104:107], v99 offset:26624
	ds_read_b128 v[108:111], v99 offset:26656
	v_sub_f32_e32 v11, v88, v1
	v_sub_f32_e32 v12, v89, v1
	v_sub_f32_e32 v13, v90, v1
	v_sub_f32_e32 v87, v100, v1
	v_sub_f32_e32 v88, v101, v1
	v_sub_f32_e32 v89, v102, v1
	v_sub_f32_e32 v90, v103, v1
	v_cvt_pk_bf16_f32 v100, v3, v4
	v_cvt_pk_bf16_f32 v101, v5, v6
	v_cvt_pk_bf16_f32 v102, v7, v8
	v_cvt_pk_bf16_f32 v103, v9, v10
	v_exp_f32_e32 v11, v11
	v_exp_f32_e32 v12, v12
	s_waitcnt lgkmcnt(1)
	v_mfma_f32_32x32x16_bf16 v[32:47], v[104:107], v[100:103], v[32:47]
	ds_read_b128 v[104:107], v99 offset:35328
	v_exp_f32_e32 v13, v13
	v_exp_f32_e32 v14, v14
	v_exp_f32_e32 v15, v15
	v_exp_f32_e32 v80, v80
	v_exp_f32_e32 v81, v81
	v_exp_f32_e32 v82, v82
	s_waitcnt lgkmcnt(0)
	v_mfma_f32_32x32x16_bf16 v[16:31], v[104:107], v[100:103], v[16:31]
	ds_read_b128 v[104:107], v99 offset:35360
	v_cvt_pk_bf16_f32 v100, v11, v12
	v_cvt_pk_bf16_f32 v101, v13, v14
	v_cvt_pk_bf16_f32 v102, v15, v80
	v_cvt_pk_bf16_f32 v103, v81, v82
	v_exp_f32_e32 v83, v83
	v_exp_f32_e32 v84, v84
	v_mfma_f32_32x32x16_bf16 v[32:47], v[108:111], v[100:103], v[32:47]
	v_exp_f32_e32 v85, v85
	v_exp_f32_e32 v86, v86
	v_exp_f32_e32 v87, v87
	v_exp_f32_e32 v88, v88
	v_exp_f32_e32 v89, v89
	v_exp_f32_e32 v90, v90
	v_exp_f32_e32 v91, v91
	s_waitcnt lgkmcnt(0)
	v_mfma_f32_32x32x16_bf16 v[16:31], v[104:107], v[100:103], v[16:31]
	v_exp_f32_e32 v92, v92
	v_exp_f32_e32 v93, v93
	v_exp_f32_e32 v94, v94
	v_exp_f32_e32 v95, v95
	v_exp_f32_e32 v96, v96
	v_exp_f32_e32 v97, v97
	v_exp_f32_e32 v98, v98
	s_and_saveexec_b64 s[70:71], s[52:53]
	s_cbranch_execz .Lpv_skip_3
	ds_read_b128 v[100:103], v99 offset:26688
	ds_read_b128 v[212:215], v99 offset:35392
	ds_read_b128 v[216:219], v99 offset:26720
	ds_read_b128 v[220:223], v99 offset:35424
	v_cvt_pk_bf16_f32 v104, v83, v84
	v_cvt_pk_bf16_f32 v105, v85, v86
	v_cvt_pk_bf16_f32 v106, v87, v88
	v_cvt_pk_bf16_f32 v107, v89, v90
	s_waitcnt lgkmcnt(3)
	s_nop 0
	v_mfma_f32_32x32x16_bf16 v[32:47], v[100:103], v[104:107], v[32:47]
	v_sub_f32_e32 v48, v48, v1
	v_sub_f32_e32 v49, v49, v1
	v_sub_f32_e32 v50, v50, v1
	v_sub_f32_e32 v51, v51, v1
	v_sub_f32_e32 v52, v52, v1
	v_sub_f32_e32 v53, v53, v1
	v_sub_f32_e32 v54, v54, v1
	v_sub_f32_e32 v55, v55, v1
	s_waitcnt lgkmcnt(2)
	v_mfma_f32_32x32x16_bf16 v[16:31], v[212:215], v[104:107], v[16:31]
	v_sub_f32_e32 v56, v56, v1
	v_sub_f32_e32 v57, v57, v1
	v_sub_f32_e32 v58, v58, v1
	v_sub_f32_e32 v59, v59, v1
	v_sub_f32_e32 v60, v60, v1
	v_sub_f32_e32 v61, v61, v1
	v_sub_f32_e32 v62, v62, v1
	v_sub_f32_e32 v63, v63, v1
	v_cvt_pk_bf16_f32 v104, v91, v92
	v_cvt_pk_bf16_f32 v105, v93, v94
	v_cvt_pk_bf16_f32 v106, v95, v96
	v_cvt_pk_bf16_f32 v107, v97, v98
	s_waitcnt lgkmcnt(1)
	s_nop 0
	v_mfma_f32_32x32x16_bf16 v[32:47], v[216:219], v[104:107], v[32:47]
	v_exp_f32_e32 v48, v48
	v_exp_f32_e32 v49, v49
	v_exp_f32_e32 v50, v50
	v_exp_f32_e32 v51, v51
	v_exp_f32_e32 v52, v52
	v_exp_f32_e32 v53, v53
	v_exp_f32_e32 v54, v54
	v_exp_f32_e32 v55, v55
	s_waitcnt lgkmcnt(0)
	v_mfma_f32_32x32x16_bf16 v[16:31], v[220:223], v[104:107], v[16:31]
	v_exp_f32_e32 v56, v56
	v_exp_f32_e32 v57, v57
	v_exp_f32_e32 v58, v58
	v_exp_f32_e32 v59, v59
	v_exp_f32_e32 v60, v60
	v_exp_f32_e32 v61, v61
	v_exp_f32_e32 v62, v62
	v_exp_f32_e32 v63, v63
.LBB0_273:
	s_or_b64 exec, exec, s[70:71]
	s_and_saveexec_b64 s[52:53], s[50:51]
	s_cbranch_execz .Lpv_skip_2
	ds_read_b128 v[100:103], v99 offset:26752
	ds_read_b128 v[212:215], v99 offset:35456
	ds_read_b128 v[216:219], v99 offset:26784
	ds_read_b128 v[220:223], v99 offset:35488
	v_cvt_pk_bf16_f32 v104, v48, v49
	v_cvt_pk_bf16_f32 v105, v50, v51
	v_cvt_pk_bf16_f32 v106, v52, v53
	v_cvt_pk_bf16_f32 v107, v54, v55
	s_waitcnt lgkmcnt(3)
	s_nop 0
	v_mfma_f32_32x32x16_bf16 v[32:47], v[100:103], v[104:107], v[32:47]
	v_sub_f32_e32 v64, v64, v1
	v_sub_f32_e32 v65, v65, v1
	v_sub_f32_e32 v66, v66, v1
	v_sub_f32_e32 v67, v67, v1
	v_sub_f32_e32 v68, v68, v1
	v_sub_f32_e32 v69, v69, v1
	v_sub_f32_e32 v70, v70, v1
	v_sub_f32_e32 v71, v71, v1
	s_waitcnt lgkmcnt(2)
	v_mfma_f32_32x32x16_bf16 v[16:31], v[212:215], v[104:107], v[16:31]
	v_sub_f32_e32 v72, v72, v1
	v_sub_f32_e32 v73, v73, v1
	v_sub_f32_e32 v74, v74, v1
	v_sub_f32_e32 v75, v75, v1
	v_sub_f32_e32 v76, v76, v1
	v_sub_f32_e32 v77, v77, v1
	v_sub_f32_e32 v78, v78, v1
	v_sub_f32_e32 v79, v79, v1
	v_cvt_pk_bf16_f32 v104, v56, v57
	v_cvt_pk_bf16_f32 v105, v58, v59
	v_cvt_pk_bf16_f32 v106, v60, v61
	v_cvt_pk_bf16_f32 v107, v62, v63
	s_waitcnt lgkmcnt(1)
	s_nop 0
	v_mfma_f32_32x32x16_bf16 v[32:47], v[216:219], v[104:107], v[32:47]
	v_exp_f32_e32 v64, v64
	v_exp_f32_e32 v65, v65
	v_exp_f32_e32 v66, v66
	v_exp_f32_e32 v67, v67
	v_exp_f32_e32 v68, v68
	v_exp_f32_e32 v69, v69
	v_exp_f32_e32 v70, v70
	v_exp_f32_e32 v71, v71
	s_waitcnt lgkmcnt(0)
	v_mfma_f32_32x32x16_bf16 v[16:31], v[220:223], v[104:107], v[16:31]
	v_exp_f32_e32 v72, v72
	v_exp_f32_e32 v73, v73
	v_exp_f32_e32 v74, v74
	v_exp_f32_e32 v75, v75
	v_exp_f32_e32 v76, v76
	v_exp_f32_e32 v77, v77
	v_exp_f32_e32 v78, v78
	v_exp_f32_e32 v79, v79

.LBB0_292:
	v_sub_f32_e32 v3, v80, v1
	v_sub_f32_e32 v4, v81, v1
	v_sub_f32_e32 v5, v82, v1
	v_sub_f32_e32 v6, v83, v1
	v_sub_f32_e32 v7, v84, v1
	v_sub_f32_e32 v8, v85, v1
	v_sub_f32_e32 v9, v86, v1
	v_sub_f32_e32 v10, v87, v1
	v_exp_f32_e32 v3, v3
	v_exp_f32_e32 v4, v4
	v_exp_f32_e32 v5, v5
	v_exp_f32_e32 v6, v6
	v_exp_f32_e32 v7, v7
	v_exp_f32_e32 v8, v8
	v_exp_f32_e32 v9, v9
	v_exp_f32_e32 v10, v10
	v_sub_f32_e32 v86, v99, v1
	v_add_u32_e32 v99, v239, v230
	v_sub_f32_e32 v14, v91, v1
	v_sub_f32_e32 v15, v92, v1
	v_sub_f32_e32 v80, v93, v1
	v_sub_f32_e32 v81, v94, v1
	v_sub_f32_e32 v82, v95, v1
	v_sub_f32_e32 v83, v96, v1
	v_sub_f32_e32 v84, v97, v1
	v_sub_f32_e32 v85, v98, v1
	v_sub_f32_e32 v91, v104, v1
	v_sub_f32_e32 v92, v105, v1
	v_sub_f32_e32 v93, v106, v1
	v_sub_f32_e32 v94, v107, v1
	v_sub_f32_e32 v95, v108, v1
	v_sub_f32_e32 v96, v109, v1
	v_sub_f32_e32 v97, v110, v1
	v_sub_f32_e32 v98, v111, v1
	ds_read_b128 v[104:107], v99 offset:26624
	ds_read_b128 v[108:111], v99 offset:26656
	v_sub_f32_e32 v11, v88, v1
	v_sub_f32_e32 v12, v89, v1
	v_sub_f32_e32 v13, v90, v1
	v_sub_f32_e32 v87, v100, v1
	v_sub_f32_e32 v88, v101, v1
	v_sub_f32_e32 v89, v102, v1
	v_sub_f32_e32 v90, v103, v1
	v_cvt_pk_bf16_f32 v100, v3, v4
	v_cvt_pk_bf16_f32 v101, v5, v6
	v_cvt_pk_bf16_f32 v102, v7, v8
	v_cvt_pk_bf16_f32 v103, v9, v10
	v_exp_f32_e32 v11, v11
	v_exp_f32_e32 v12, v12
	s_waitcnt lgkmcnt(1)
	v_mfma_f32_32x32x16_bf16 v[32:47], v[104:107], v[100:103], v[32:47]
	ds_read_b128 v[104:107], v99 offset:35328
	v_exp_f32_e32 v13, v13
	v_exp_f32_e32 v14, v14
	v_exp_f32_e32 v15, v15
	v_exp_f32_e32 v80, v80
	v_exp_f32_e32 v81, v81
	v_exp_f32_e32 v82, v82
	s_waitcnt lgkmcnt(0)
	v_mfma_f32_32x32x16_bf16 v[16:31], v[104:107], v[100:103], v[16:31]
	ds_read_b128 v[104:107], v99 offset:35360
	v_cvt_pk_bf16_f32 v100, v11, v12
	v_cvt_pk_bf16_f32 v101, v13, v14
	v_cvt_pk_bf16_f32 v102, v15, v80
	v_cvt_pk_bf16_f32 v103, v81, v82
	v_exp_f32_e32 v83, v83
	v_exp_f32_e32 v84, v84
	v_mfma_f32_32x32x16_bf16 v[32:47], v[108:111], v[100:103], v[32:47]
	v_exp_f32_e32 v85, v85
	v_exp_f32_e32 v86, v86
	v_exp_f32_e32 v87, v87
	v_exp_f32_e32 v88, v88
	v_exp_f32_e32 v89, v89
	v_exp_f32_e32 v90, v90
	v_exp_f32_e32 v91, v91
	s_waitcnt lgkmcnt(0)
	v_mfma_f32_32x32x16_bf16 v[16:31], v[104:107], v[100:103], v[16:31]
	v_exp_f32_e32 v92, v92
	v_exp_f32_e32 v93, v93
	v_exp_f32_e32 v94, v94
	v_exp_f32_e32 v95, v95
	v_exp_f32_e32 v96, v96
	v_exp_f32_e32 v97, v97
	v_exp_f32_e32 v98, v98
	s_and_saveexec_b64 s[64:65], s[52:53]
	s_cbranch_execz .Lpv_skip_1
	ds_read_b128 v[100:103], v99 offset:26688
	ds_read_b128 v[212:215], v99 offset:35392
	ds_read_b128 v[216:219], v99 offset:26720
	ds_read_b128 v[220:223], v99 offset:35424
	v_cvt_pk_bf16_f32 v104, v83, v84
	v_cvt_pk_bf16_f32 v105, v85, v86
	v_cvt_pk_bf16_f32 v106, v87, v88
	v_cvt_pk_bf16_f32 v107, v89, v90
	s_waitcnt lgkmcnt(3)
	s_nop 0
	v_mfma_f32_32x32x16_bf16 v[32:47], v[100:103], v[104:107], v[32:47]
	v_sub_f32_e32 v48, v48, v1
	v_sub_f32_e32 v49, v49, v1
	v_sub_f32_e32 v50, v50, v1
	v_sub_f32_e32 v51, v51, v1
	v_sub_f32_e32 v52, v52, v1
	v_sub_f32_e32 v53, v53, v1
	v_sub_f32_e32 v54, v54, v1
	v_sub_f32_e32 v55, v55, v1
	s_waitcnt lgkmcnt(2)
	v_mfma_f32_32x32x16_bf16 v[16:31], v[212:215], v[104:107], v[16:31]
	v_sub_f32_e32 v56, v56, v1
	v_sub_f32_e32 v57, v57, v1
	v_sub_f32_e32 v58, v58, v1
	v_sub_f32_e32 v59, v59, v1
	v_sub_f32_e32 v60, v60, v1
	v_sub_f32_e32 v61, v61, v1
	v_sub_f32_e32 v62, v62, v1
	v_sub_f32_e32 v63, v63, v1
	v_cvt_pk_bf16_f32 v104, v91, v92
	v_cvt_pk_bf16_f32 v105, v93, v94
	v_cvt_pk_bf16_f32 v106, v95, v96
	v_cvt_pk_bf16_f32 v107, v97, v98
	s_waitcnt lgkmcnt(1)
	s_nop 0
	v_mfma_f32_32x32x16_bf16 v[32:47], v[216:219], v[104:107], v[32:47]
	v_exp_f32_e32 v48, v48
	v_exp_f32_e32 v49, v49
	v_exp_f32_e32 v50, v50
	v_exp_f32_e32 v51, v51
	v_exp_f32_e32 v52, v52
	v_exp_f32_e32 v53, v53
	v_exp_f32_e32 v54, v54
	v_exp_f32_e32 v55, v55
	s_waitcnt lgkmcnt(0)
	v_mfma_f32_32x32x16_bf16 v[16:31], v[220:223], v[104:107], v[16:31]
	v_exp_f32_e32 v56, v56
	v_exp_f32_e32 v57, v57
	v_exp_f32_e32 v58, v58
	v_exp_f32_e32 v59, v59
	v_exp_f32_e32 v60, v60
	v_exp_f32_e32 v61, v61
	v_exp_f32_e32 v62, v62
	v_exp_f32_e32 v63, v63
.LBB0_294:
	s_or_b64 exec, exec, s[64:65]
	s_and_saveexec_b64 s[52:53], s[50:51]
	s_cbranch_execz .Lpv_skip_0
	ds_read_b128 v[100:103], v99 offset:26752
	ds_read_b128 v[212:215], v99 offset:35456
	ds_read_b128 v[216:219], v99 offset:26784
	ds_read_b128 v[220:223], v99 offset:35488
	v_cvt_pk_bf16_f32 v104, v48, v49
	v_cvt_pk_bf16_f32 v105, v50, v51
	v_cvt_pk_bf16_f32 v106, v52, v53
	v_cvt_pk_bf16_f32 v107, v54, v55
	s_waitcnt lgkmcnt(3)
	s_nop 0
	v_mfma_f32_32x32x16_bf16 v[32:47], v[100:103], v[104:107], v[32:47]
	v_sub_f32_e32 v64, v64, v1
	v_sub_f32_e32 v65, v65, v1
	v_sub_f32_e32 v66, v66, v1
	v_sub_f32_e32 v67, v67, v1
	v_sub_f32_e32 v68, v68, v1
	v_sub_f32_e32 v69, v69, v1
	v_sub_f32_e32 v70, v70, v1
	v_sub_f32_e32 v71, v71, v1
	s_waitcnt lgkmcnt(2)
	v_mfma_f32_32x32x16_bf16 v[16:31], v[212:215], v[104:107], v[16:31]
	v_sub_f32_e32 v72, v72, v1
	v_sub_f32_e32 v73, v73, v1
	v_sub_f32_e32 v74, v74, v1
	v_sub_f32_e32 v75, v75, v1
	v_sub_f32_e32 v76, v76, v1
	v_sub_f32_e32 v77, v77, v1
	v_sub_f32_e32 v78, v78, v1
	v_sub_f32_e32 v79, v79, v1
	v_cvt_pk_bf16_f32 v104, v56, v57
	v_cvt_pk_bf16_f32 v105, v58, v59
	v_cvt_pk_bf16_f32 v106, v60, v61
	v_cvt_pk_bf16_f32 v107, v62, v63
	s_waitcnt lgkmcnt(1)
	s_nop 0
	v_mfma_f32_32x32x16_bf16 v[32:47], v[216:219], v[104:107], v[32:47]
	v_exp_f32_e32 v64, v64
	v_exp_f32_e32 v65, v65
	v_exp_f32_e32 v66, v66
	v_exp_f32_e32 v67, v67
	v_exp_f32_e32 v68, v68
	v_exp_f32_e32 v69, v69
	v_exp_f32_e32 v70, v70
	v_exp_f32_e32 v71, v71
	s_waitcnt lgkmcnt(0)
	v_mfma_f32_32x32x16_bf16 v[16:31], v[220:223], v[104:107], v[16:31]
	v_exp_f32_e32 v72, v72
	v_exp_f32_e32 v73, v73
	v_exp_f32_e32 v74, v74
	v_exp_f32_e32 v75, v75
	v_exp_f32_e32 v76, v76
	v_exp_f32_e32 v77, v77
	v_exp_f32_e32 v78, v78
	v_exp_f32_e32 v79, v79
.LBB0_296:
	s_or_b64 exec, exec, s[52:53]
	s_and_saveexec_b64 s[50:51], s[48:49]
	s_cbranch_execz .Lrs_skip_2
	ds_read_b128 v[100:103], v99 offset:26816
	ds_read_b128 v[212:215], v99 offset:35520
	ds_read_b128 v[216:219], v99 offset:26848
	ds_read_b128 v[220:223], v99 offset:35552
	v_cvt_pk_bf16_f32 v104, v64, v65
	v_cvt_pk_bf16_f32 v105, v66, v67
	v_cvt_pk_bf16_f32 v106, v68, v69
	v_cvt_pk_bf16_f32 v107, v70, v71
	s_waitcnt lgkmcnt(3)
	s_nop 0
	v_mfma_f32_32x32x16_bf16 v[32:47], v[100:103], v[104:107], v[32:47]
	v_add_f32_e32 v3, v3, v4
	v_add_f32_e32 v5, v5, v6
	v_add_f32_e32 v7, v7, v8
	v_add_f32_e32 v9, v9, v10
	v_add_f32_e32 v11, v11, v12
	v_add_f32_e32 v13, v13, v14
	v_add_f32_e32 v15, v15, v80
	v_add_f32_e32 v81, v81, v82
	s_waitcnt lgkmcnt(2)
	v_mfma_f32_32x32x16_bf16 v[16:31], v[212:215], v[104:107], v[16:31]
	v_add_f32_e32 v83, v83, v84
	v_add_f32_e32 v85, v85, v86
	v_add_f32_e32 v87, v87, v88
	v_add_f32_e32 v89, v89, v90
	v_add_f32_e32 v91, v91, v92
	v_add_f32_e32 v93, v93, v94
	v_add_f32_e32 v95, v95, v96
	v_add_f32_e32 v97, v97, v98
	v_cvt_pk_bf16_f32 v104, v72, v73
	v_cvt_pk_bf16_f32 v105, v74, v75
	v_cvt_pk_bf16_f32 v106, v76, v77
	v_cvt_pk_bf16_f32 v107, v78, v79
	s_waitcnt lgkmcnt(1)
	s_nop 0
	v_mfma_f32_32x32x16_bf16 v[32:47], v[216:219], v[104:107], v[32:47]
	v_add_f32_e32 v48, v48, v49
	v_add_f32_e32 v50, v50, v51
	v_add_f32_e32 v52, v52, v53
	v_add_f32_e32 v54, v54, v55
	v_add_f32_e32 v56, v56, v57
	v_add_f32_e32 v58, v58, v59
	v_add_f32_e32 v60, v60, v61
	v_add_f32_e32 v62, v62, v63
	s_waitcnt lgkmcnt(0)
	v_mfma_f32_32x32x16_bf16 v[16:31], v[220:223], v[104:107], v[16:31]
	v_add_f32_e32 v64, v64, v65
	v_add_f32_e32 v66, v66, v67
	v_add_f32_e32 v68, v68, v69
	v_add_f32_e32 v70, v70, v71
	v_add_f32_e32 v72, v72, v73
	v_add_f32_e32 v74, v74, v75
	v_add_f32_e32 v76, v76, v77
	v_add_f32_e32 v78, v78, v79
	v_add_f32_e32 v3, v3, v5
	v_add_f32_e32 v7, v7, v9
	v_add_f32_e32 v11, v11, v13
	v_add_f32_e32 v15, v15, v81
	v_add_f32_e32 v83, v83, v85
	v_add_f32_e32 v87, v87, v89
	v_add_f32_e32 v91, v91, v93
	v_add_f32_e32 v95, v95, v97
	v_add_f32_e32 v48, v48, v50
	v_add_f32_e32 v52, v52, v54
	v_add_f32_e32 v56, v56, v58
	v_add_f32_e32 v60, v60, v62
	v_add_f32_e32 v64, v64, v66
	v_add_f32_e32 v68, v68, v70
	v_add_f32_e32 v72, v72, v74
	v_add_f32_e32 v76, v76, v78
	v_add_f32_e32 v3, v3, v7
	v_add_f32_e32 v11, v11, v15
	v_add_f32_e32 v83, v83, v87
	v_add_f32_e32 v91, v91, v95
	v_add_f32_e32 v48, v48, v52
	v_add_f32_e32 v56, v56, v60
	v_add_f32_e32 v64, v64, v68
	v_add_f32_e32 v72, v72, v76
	v_add_f32_e32 v3, v3, v11
	v_add_f32_e32 v83, v83, v91
	v_add_f32_e32 v48, v48, v56
	v_add_f32_e32 v64, v64, v72
	v_add_f32_e32 v3, v3, v83
	v_add_f32_e32 v48, v48, v64
	v_add_f32_e32 v3, v3, v48
	s_branch .LBB0_238
.Lrs_skip_0:
	s_or_b64 exec, exec, s[50:51]
	v_add_f32_e32 v3, v3, v4
	v_add_f32_e32 v5, v5, v6
	v_add_f32_e32 v7, v7, v8
	v_add_f32_e32 v9, v9, v10
	v_add_f32_e32 v11, v11, v12
	v_add_f32_e32 v13, v13, v14
	v_add_f32_e32 v15, v15, v80
	v_add_f32_e32 v81, v81, v82
	v_add_f32_e32 v83, v83, v84
	v_add_f32_e32 v85, v85, v86
	v_add_f32_e32 v87, v87, v88
	v_add_f32_e32 v89, v89, v90
	v_add_f32_e32 v91, v91, v92
	v_add_f32_e32 v93, v93, v94
	v_add_f32_e32 v95, v95, v96
	v_add_f32_e32 v97, v97, v98
	v_add_f32_e32 v48, v48, v49
	v_add_f32_e32 v50, v50, v51
	v_add_f32_e32 v52, v52, v53
	v_add_f32_e32 v54, v54, v55
	v_add_f32_e32 v56, v56, v57
	v_add_f32_e32 v58, v58, v59
	v_add_f32_e32 v60, v60, v61
	v_add_f32_e32 v62, v62, v63
	v_add_f32_e32 v64, v64, v65
	v_add_f32_e32 v66, v66, v67
	v_add_f32_e32 v68, v68, v69
	v_add_f32_e32 v70, v70, v71
	v_add_f32_e32 v72, v72, v73
	v_add_f32_e32 v74, v74, v75
	v_add_f32_e32 v76, v76, v77
	v_add_f32_e32 v78, v78, v79
	v_add_f32_e32 v3, v3, v5
	v_add_f32_e32 v7, v7, v9
	v_add_f32_e32 v11, v11, v13
	v_add_f32_e32 v15, v15, v81
	v_add_f32_e32 v83, v83, v85
	v_add_f32_e32 v87, v87, v89
	v_add_f32_e32 v91, v91, v93
	v_add_f32_e32 v95, v95, v97
	v_add_f32_e32 v48, v48, v50
	v_add_f32_e32 v52, v52, v54
	v_add_f32_e32 v56, v56, v58
	v_add_f32_e32 v60, v60, v62
	v_add_f32_e32 v64, v64, v66
	v_add_f32_e32 v68, v68, v70
	v_add_f32_e32 v72, v72, v74
	v_add_f32_e32 v76, v76, v78
	v_add_f32_e32 v3, v3, v7
	v_add_f32_e32 v11, v11, v15
	v_add_f32_e32 v83, v83, v87
	v_add_f32_e32 v91, v91, v95
	v_add_f32_e32 v48, v48, v52
	v_add_f32_e32 v56, v56, v60
	v_add_f32_e32 v64, v64, v68
	v_add_f32_e32 v72, v72, v76
	v_add_f32_e32 v3, v3, v11
	v_add_f32_e32 v83, v83, v91
	v_add_f32_e32 v48, v48, v56
	v_add_f32_e32 v64, v64, v72
	v_add_f32_e32 v3, v3, v83
	v_add_f32_e32 v48, v48, v64
	v_add_f32_e32 v3, v3, v48
	s_branch .LBB0_277

.Lpv_skip_0:
	s_or_b64 exec, exec, s[52:53]
	v_mov_b32_e32 v64, 0
	v_mov_b32_e32 v65, 0
	v_mov_b32_e32 v66, 0
	v_mov_b32_e32 v67, 0
	v_mov_b32_e32 v68, 0
	v_mov_b32_e32 v69, 0
	v_mov_b32_e32 v70, 0
	v_mov_b32_e32 v71, 0
	v_mov_b32_e32 v72, 0
	v_mov_b32_e32 v73, 0
	v_mov_b32_e32 v74, 0
	v_mov_b32_e32 v75, 0
	v_mov_b32_e32 v76, 0
	v_mov_b32_e32 v77, 0
	v_mov_b32_e32 v78, 0
	v_mov_b32_e32 v79, 0
	s_branch .LBB0_296
.Lpv_skip_1:
	s_or_b64 exec, exec, s[64:65]
	v_mov_b32_e32 v48, 0
	v_mov_b32_e32 v49, 0
	v_mov_b32_e32 v50, 0
	v_mov_b32_e32 v51, 0
	v_mov_b32_e32 v52, 0
	v_mov_b32_e32 v53, 0
	v_mov_b32_e32 v54, 0
	v_mov_b32_e32 v55, 0
	v_mov_b32_e32 v56, 0
	v_mov_b32_e32 v57, 0
	v_mov_b32_e32 v58, 0
	v_mov_b32_e32 v59, 0
	v_mov_b32_e32 v60, 0
	v_mov_b32_e32 v61, 0
	v_mov_b32_e32 v62, 0
	v_mov_b32_e32 v63, 0
	s_branch .LBB0_294

.Lpv_skip_3:
	s_or_b64 exec, exec, s[70:71]
	v_mov_b32_e32 v48, 0
	v_mov_b32_e32 v49, 0
	v_mov_b32_e32 v50, 0
	v_mov_b32_e32 v51, 0
	v_mov_b32_e32 v52, 0
	v_mov_b32_e32 v53, 0
	v_mov_b32_e32 v54, 0
	v_mov_b32_e32 v55, 0
	v_mov_b32_e32 v56, 0
	v_mov_b32_e32 v57, 0
	v_mov_b32_e32 v58, 0
	v_mov_b32_e32 v59, 0
	v_mov_b32_e32 v60, 0
	v_mov_b32_e32 v61, 0
	v_mov_b32_e32 v62, 0
	v_mov_b32_e32 v63, 0
	s_branch .LBB0_273

.Lpv_skip_5:
	s_or_b64 exec, exec, s[56:57]
	v_mov_b32_e32 v48, 0
	v_mov_b32_e32 v49, 0
	v_mov_b32_e32 v50, 0
	v_mov_b32_e32 v51, 0
	v_mov_b32_e32 v52, 0
	v_mov_b32_e32 v53, 0
	v_mov_b32_e32 v54, 0
	v_mov_b32_e32 v55, 0
	v_mov_b32_e32 v56, 0
	v_mov_b32_e32 v57, 0
	v_mov_b32_e32 v58, 0
	v_mov_b32_e32 v59, 0
	v_mov_b32_e32 v60, 0
	v_mov_b32_e32 v61, 0
	v_mov_b32_e32 v62, 0
	v_mov_b32_e32 v63, 0
	s_branch .LBB0_254
